# phase_ych (channel-DFT GEMV before the projections): all 8 per-wave dot products issue their loads up front and reduce together instead of 8 serial load-reduce-store rounds; on top of v12
# speedup vs baseline: 1.0051x; 1.0051x over previous
; __device__ __forceinline__ float bf_lo(unsigned u) { return __uint_as_float(u << 16); }
; __device__ __forceinline__ float bf_hi(unsigned u) { return __uint_as_float(u & 0xffff0000u); }
; __device__ __forceinline__ void phase_ych(const bf16_t* A2, const bf16_t* Wc, float* YCH) {
;     int tid_ = threadIdx.x; asm volatile("" : "+v"(tid_));
;     const int wid = tid_ >> 6, lane = tid_ & 63;
;     for (int o = blockIdx.x * 8 + wid; o < 32 * 512; o += gridDim.x * 8) {
;         const int b = o >> 9, gm = o & 511;
;         const bf16_t* a = A2 + ((size_t)b * 2048 + 1024) * DM + lane * 16; const bf16_t* w = Wc + (size_t)gm * DM + lane * 16;
;         float acc = 0.f;
; #pragma unroll
;         for (int q = 0; q < 2; ++q) { const u32x4 av = *(const u32x4*)(a + q * 8), wv = *(const u32x4*)(w + q * 8);
;             acc += bf_lo(av.x) * bf_lo(wv.x) + bf_hi(av.x) * bf_hi(wv.x) + bf_lo(av.y) * bf_lo(wv.y) + bf_hi(av.y) * bf_hi(wv.y) + bf_lo(av.z) * bf_lo(wv.z) + bf_hi(av.z) * bf_hi(wv.z) + bf_lo(av.w) * bf_lo(wv.w) + bf_hi(av.w) * bf_hi(wv.w); }
; #pragma unroll
;         for (int sft = 32; sft >= 1; sft >>= 1) acc += __shfl_xor(acc, sft);
.LBB0_565:
	s_or_b64 exec, exec, s[0:1]
	s_add_u32 s14, s72, 0x2580000
	v_mov_b32_e32 v2, v200
	s_waitcnt lgkmcnt(0)
	s_barrier
	s_addc_u32 s15, s73, 0
	s_add_u32 s60, s72, 0x33ad000
	v_ashrrev_i32_e32 v1, 6, v2
	v_add_u32_e32 v0, s48, v1
	s_movk_i32 s0, 0x4000
	s_addc_u32 s61, s73, 0
	v_cmp_gt_i32_e32 vcc, s0, v0
	s_and_saveexec_b64 s[0:1], vcc
	s_cbranch_execz .LBB0_570
	v_and_b32_e32 v7, 63, v2
	v_mov_b32_e32 v3, 0
	v_lshlrev_b32_e32 v2, 5, v7
	v_lshl_add_u64 v[4:5], s[14:15], 0, v[2:3]
	v_mbcnt_hi_u32_b32 v2, -1, v201
	v_and_b32_e32 v8, 64, v2
	v_lshlrev_b32_e32 v6, 4, v7
	v_add_u32_e32 v13, 64, v8
	v_cmp_eq_u32_e64 s[2:3], 0, v7
	v_xor_b32_e32 v7, 32, v2
	v_cmp_lt_i32_e32 vcc, v7, v13
	v_lshlrev_b32_e32 v1, 10, v1
	s_lshl_b32 s16, s76, 3
	v_cndmask_b32_e32 v7, v2, v7, vcc
	v_lshlrev_b32_e32 v8, 2, v7
	v_xor_b32_e32 v7, 16, v2
	v_cmp_lt_i32_e32 vcc, v7, v13
	v_lshl_add_u32 v14, s50, 13, v1
	s_lshl_b32 s17, s76, 13
	v_cndmask_b32_e32 v7, v2, v7, vcc
	v_lshlrev_b32_e32 v9, 2, v7
	v_xor_b32_e32 v7, 8, v2
	v_cmp_lt_i32_e32 vcc, v7, v13
	s_mov_b64 s[4:5], 0
	v_lshlrev_b32_e32 v6, 1, v6
	v_cndmask_b32_e32 v7, v2, v7, vcc
	v_lshlrev_b32_e32 v10, 2, v7
	v_xor_b32_e32 v7, 4, v2
	v_cmp_lt_i32_e32 vcc, v7, v13
	s_mov_b64 s[6:7], 0x200000
	s_movk_i32 s18, 0x3fff
	v_cndmask_b32_e32 v7, v2, v7, vcc
	v_lshlrev_b32_e32 v11, 2, v7
	v_xor_b32_e32 v7, 2, v2
	v_cmp_lt_i32_e32 vcc, v7, v13
	s_nop 1
	v_cndmask_b32_e32 v7, v2, v7, vcc
	v_lshlrev_b32_e32 v12, 2, v7
	v_xor_b32_e32 v7, 1, v2
	v_cmp_lt_i32_e32 vcc, v7, v13
	s_nop 1
	v_cndmask_b32_e32 v2, v2, v7, vcc
	v_lshlrev_b32_e32 v13, 2, v2
	v_mov_b32_e32 v7, v3
	s_cmp_eq_u32 s76, 0x100
	s_cbranch_scc1 .Lych_fast
	s_branch .LBB0_568

; __device__ __forceinline__ float bf_lo(unsigned u) { return __uint_as_float(u << 16); }
; __device__ __forceinline__ float bf_hi(unsigned u) { return __uint_as_float(u & 0xffff0000u); }
; __device__ __forceinline__ void phase_ych(const bf16_t* A2, const bf16_t* Wc, float* YCH) {
;     ...
;     for (int o = blockIdx.x * 8 + wid; o < 32 * 512; o += gridDim.x * 8) {
;         const int b = o >> 9, gm = o & 511;
;         const bf16_t* a = A2 + ((size_t)b * 2048 + 1024) * DM + lane * 16; const bf16_t* w = Wc + (size_t)gm * DM + lane * 16;
;         float acc = 0.f;
; #pragma unroll
;         for (int q = 0; q < 2; ++q) { const u32x4 av = *(const u32x4*)(a + q * 8), wv = *(const u32x4*)(w + q * 8);
;             acc += bf_lo(av.x) * bf_lo(wv.x) + bf_hi(av.x) * bf_hi(wv.x) + bf_lo(av.y) * bf_lo(wv.y) + bf_hi(av.y) * bf_hi(wv.y) + bf_lo(av.z) * bf_lo(wv.z) + bf_hi(av.z) * bf_hi(wv.z) + bf_lo(av.w) * bf_lo(wv.w) + bf_hi(av.w) * bf_hi(wv.w); }
.Lych_fast:
	s_waitcnt lgkmcnt(0)
	v_and_b32_e32 v1, 0x7fc00, v14
	v_lshlrev_b32_e32 v2, 1, v1
	v_lshl_add_u64 v[152:153], v[4:5], 0, v[2:3]
	global_load_dwordx4 v[48:51], v[152:153], off
	global_load_dwordx4 v[52:55], v[152:153], off offset:16
	v_lshrrev_b32_e32 v154, 9, v0
	v_lshlrev_b32_e32 v154, 22, v154
	v_add_u32_e32 v154, v154, v6
	v_add_u32_e32 v154, 0x200000, v154
	s_mov_b64 s[4:5], s[96:97]
	global_load_dwordx4 v[56:59], v154, s[4:5]
	global_load_dwordx4 v[60:63], v154, s[4:5] offset:16
	s_add_u32 s4, s4, 0x1000000
	s_addc_u32 s5, s5, 0
	s_nop 0
	global_load_dwordx4 v[64:67], v154, s[4:5]
	global_load_dwordx4 v[68:71], v154, s[4:5] offset:16
	s_add_u32 s4, s4, 0x1000000
	s_addc_u32 s5, s5, 0
	s_nop 0
	global_load_dwordx4 v[72:75], v154, s[4:5]
	global_load_dwordx4 v[76:79], v154, s[4:5] offset:16
	s_add_u32 s4, s4, 0x1000000
	s_addc_u32 s5, s5, 0
	s_nop 0
	global_load_dwordx4 v[80:83], v154, s[4:5]
	global_load_dwordx4 v[84:87], v154, s[4:5] offset:16
	s_add_u32 s4, s4, 0x1000000
	s_addc_u32 s5, s5, 0
	s_nop 0
	global_load_dwordx4 v[88:91], v154, s[4:5]
	global_load_dwordx4 v[92:95], v154, s[4:5] offset:16
	s_add_u32 s4, s4, 0x1000000
	s_addc_u32 s5, s5, 0
	s_nop 0
	global_load_dwordx4 v[96:99], v154, s[4:5]
	global_load_dwordx4 v[100:103], v154, s[4:5] offset:16
	s_add_u32 s4, s4, 0x1000000
	s_addc_u32 s5, s5, 0
	s_nop 0
	global_load_dwordx4 v[104:107], v154, s[4:5]
	global_load_dwordx4 v[108:111], v154, s[4:5] offset:16
	s_add_u32 s4, s4, 0x1000000
	s_addc_u32 s5, s5, 0
	s_nop 0
	global_load_dwordx4 v[112:115], v154, s[4:5]
	global_load_dwordx4 v[116:119], v154, s[4:5] offset:16
	v_lshlrev_b32_e32 v155, 2, v0
	s_waitcnt vmcnt(16)
	v_lshlrev_b32_e32 v120, 16, v48
	v_and_b32_e32 v121, 0xffff0000, v48
	v_lshlrev_b32_e32 v128, 16, v52
	v_and_b32_e32 v129, 0xffff0000, v52
	v_lshlrev_b32_e32 v122, 16, v49
	v_and_b32_e32 v123, 0xffff0000, v49
	v_lshlrev_b32_e32 v130, 16, v53
	v_and_b32_e32 v131, 0xffff0000, v53
	v_lshlrev_b32_e32 v124, 16, v50
	v_and_b32_e32 v125, 0xffff0000, v50
	v_lshlrev_b32_e32 v132, 16, v54
	v_and_b32_e32 v133, 0xffff0000, v54
	v_lshlrev_b32_e32 v126, 16, v51
	v_and_b32_e32 v127, 0xffff0000, v51
	v_lshlrev_b32_e32 v134, 16, v55
	v_and_b32_e32 v135, 0xffff0000, v55
	s_waitcnt vmcnt(14)
	v_and_b32_e32 v156, 0xffff0000, v56
	v_lshlrev_b32_e32 v157, 16, v56
	v_mul_f32_e32 v136, v156, v121
	v_fmac_f32_e32 v136, v157, v120
	v_lshlrev_b32_e32 v156, 16, v57
	v_and_b32_e32 v157, 0xffff0000, v57
	v_fmac_f32_e32 v136, v156, v122
	v_fmac_f32_e32 v136, v157, v123
	v_lshlrev_b32_e32 v156, 16, v58
	v_and_b32_e32 v157, 0xffff0000, v58
	v_fmac_f32_e32 v136, v156, v124
	v_fmac_f32_e32 v136, v157, v125
	v_lshlrev_b32_e32 v156, 16, v59
	v_and_b32_e32 v157, 0xffff0000, v59
	v_fmac_f32_e32 v136, v156, v126
	v_fmac_f32_e32 v136, v157, v127
	v_and_b32_e32 v156, 0xffff0000, v60
	v_lshlrev_b32_e32 v157, 16, v60
	v_mul_f32_e32 v144, v156, v129
	v_fmac_f32_e32 v144, v157, v128
	v_lshlrev_b32_e32 v156, 16, v61
	v_and_b32_e32 v157, 0xffff0000, v61
	v_fmac_f32_e32 v144, v156, v130
	v_fmac_f32_e32 v144, v157, v131
	v_lshlrev_b32_e32 v156, 16, v62
	v_and_b32_e32 v157, 0xffff0000, v62
	v_fmac_f32_e32 v144, v156, v132
	v_fmac_f32_e32 v144, v157, v133
	v_lshlrev_b32_e32 v156, 16, v63
	v_and_b32_e32 v157, 0xffff0000, v63
	v_fmac_f32_e32 v144, v156, v134
	v_fmac_f32_e32 v144, v157, v135
	v_add_f32_e32 v136, 0, v136
	v_add_f32_e32 v136, v136, v144
	s_waitcnt vmcnt(12)
	v_and_b32_e32 v156, 0xffff0000, v64
	v_lshlrev_b32_e32 v157, 16, v64
	v_mul_f32_e32 v137, v156, v121
	v_fmac_f32_e32 v137, v157, v120
	v_lshlrev_b32_e32 v156, 16, v65
	v_and_b32_e32 v157, 0xffff0000, v65
	v_fmac_f32_e32 v137, v156, v122
	v_fmac_f32_e32 v137, v157, v123
	v_lshlrev_b32_e32 v156, 16, v66
	v_and_b32_e32 v157, 0xffff0000, v66
	v_fmac_f32_e32 v137, v156, v124
	v_fmac_f32_e32 v137, v157, v125
	v_lshlrev_b32_e32 v156, 16, v67
	v_and_b32_e32 v157, 0xffff0000, v67
	v_fmac_f32_e32 v137, v156, v126
	v_fmac_f32_e32 v137, v157, v127
	v_and_b32_e32 v156, 0xffff0000, v68
	v_lshlrev_b32_e32 v157, 16, v68
	v_mul_f32_e32 v145, v156, v129
	v_fmac_f32_e32 v145, v157, v128
	v_lshlrev_b32_e32 v156, 16, v69
	v_and_b32_e32 v157, 0xffff0000, v69
	v_fmac_f32_e32 v145, v156, v130
	v_fmac_f32_e32 v145, v157, v131
	v_lshlrev_b32_e32 v156, 16, v70
	v_and_b32_e32 v157, 0xffff0000, v70
	v_fmac_f32_e32 v145, v156, v132
	v_fmac_f32_e32 v145, v157, v133
	v_lshlrev_b32_e32 v156, 16, v71
	v_and_b32_e32 v157, 0xffff0000, v71
	v_fmac_f32_e32 v145, v156, v134
	v_fmac_f32_e32 v145, v157, v135
	v_add_f32_e32 v137, 0, v137
	v_add_f32_e32 v137, v137, v145
	s_waitcnt vmcnt(10)
	v_and_b32_e32 v156, 0xffff0000, v72
	v_lshlrev_b32_e32 v157, 16, v72
	v_mul_f32_e32 v138, v156, v121
	v_fmac_f32_e32 v138, v157, v120
	v_lshlrev_b32_e32 v156, 16, v73
	v_and_b32_e32 v157, 0xffff0000, v73
	v_fmac_f32_e32 v138, v156, v122
	v_fmac_f32_e32 v138, v157, v123
	v_lshlrev_b32_e32 v156, 16, v74
	v_and_b32_e32 v157, 0xffff0000, v74
	v_fmac_f32_e32 v138, v156, v124
	v_fmac_f32_e32 v138, v157, v125
	v_lshlrev_b32_e32 v156, 16, v75
	v_and_b32_e32 v157, 0xffff0000, v75
	v_fmac_f32_e32 v138, v156, v126
	v_fmac_f32_e32 v138, v157, v127
	v_and_b32_e32 v156, 0xffff0000, v76
	v_lshlrev_b32_e32 v157, 16, v76
	v_mul_f32_e32 v146, v156, v129
	v_fmac_f32_e32 v146, v157, v128
	v_lshlrev_b32_e32 v156, 16, v77
	v_and_b32_e32 v157, 0xffff0000, v77
	v_fmac_f32_e32 v146, v156, v130
	v_fmac_f32_e32 v146, v157, v131
	v_lshlrev_b32_e32 v156, 16, v78
	v_and_b32_e32 v157, 0xffff0000, v78
	v_fmac_f32_e32 v146, v156, v132
	v_fmac_f32_e32 v146, v157, v133
	v_lshlrev_b32_e32 v156, 16, v79
	v_and_b32_e32 v157, 0xffff0000, v79
	v_fmac_f32_e32 v146, v156, v134
	v_fmac_f32_e32 v146, v157, v135
	v_add_f32_e32 v138, 0, v138
	v_add_f32_e32 v138, v138, v146
	s_waitcnt vmcnt(8)
; __device__ __forceinline__ float bf_lo(unsigned u) { return __uint_as_float(u << 16); }
; __device__ __forceinline__ float bf_hi(unsigned u) { return __uint_as_float(u & 0xffff0000u); }
; __device__ __forceinline__ void phase_ych(const bf16_t* A2, const bf16_t* Wc, float* YCH) {
;     ...
;         const bf16_t* a = A2 + ((size_t)b * 2048 + 1024) * DM + lane * 16; const bf16_t* w = Wc + (size_t)gm * DM + lane * 16;
;         float acc = 0.f;
; #pragma unroll
;         for (int q = 0; q < 2; ++q) { const u32x4 av = *(const u32x4*)(a + q * 8), wv = *(const u32x4*)(w + q * 8);
;             acc += bf_lo(av.x) * bf_lo(wv.x) + bf_hi(av.x) * bf_hi(wv.x) + bf_lo(av.y) * bf_lo(wv.y) + bf_hi(av.y) * bf_hi(wv.y) + bf_lo(av.z) * bf_lo(wv.z) + bf_hi(av.z) * bf_hi(wv.z) + bf_lo(av.w) * bf_lo(wv.w) + bf_hi(av.w) * bf_hi(wv.w); }
	v_and_b32_e32 v156, 0xffff0000, v80
	v_lshlrev_b32_e32 v157, 16, v80
	v_mul_f32_e32 v139, v156, v121
	v_fmac_f32_e32 v139, v157, v120
	v_lshlrev_b32_e32 v156, 16, v81
	v_and_b32_e32 v157, 0xffff0000, v81
	v_fmac_f32_e32 v139, v156, v122
	v_fmac_f32_e32 v139, v157, v123
	v_lshlrev_b32_e32 v156, 16, v82
	v_and_b32_e32 v157, 0xffff0000, v82
	v_fmac_f32_e32 v139, v156, v124
	v_fmac_f32_e32 v139, v157, v125
	v_lshlrev_b32_e32 v156, 16, v83
	v_and_b32_e32 v157, 0xffff0000, v83
	v_fmac_f32_e32 v139, v156, v126
	v_fmac_f32_e32 v139, v157, v127
	v_and_b32_e32 v156, 0xffff0000, v84
	v_lshlrev_b32_e32 v157, 16, v84
	v_mul_f32_e32 v147, v156, v129
	v_fmac_f32_e32 v147, v157, v128
	v_lshlrev_b32_e32 v156, 16, v85
	v_and_b32_e32 v157, 0xffff0000, v85
	v_fmac_f32_e32 v147, v156, v130
	v_fmac_f32_e32 v147, v157, v131
	v_lshlrev_b32_e32 v156, 16, v86
	v_and_b32_e32 v157, 0xffff0000, v86
	v_fmac_f32_e32 v147, v156, v132
	v_fmac_f32_e32 v147, v157, v133
	v_lshlrev_b32_e32 v156, 16, v87
	v_and_b32_e32 v157, 0xffff0000, v87
	v_fmac_f32_e32 v147, v156, v134
	v_fmac_f32_e32 v147, v157, v135
	v_add_f32_e32 v139, 0, v139
	v_add_f32_e32 v139, v139, v147
	s_waitcnt vmcnt(6)
	v_and_b32_e32 v156, 0xffff0000, v88
	v_lshlrev_b32_e32 v157, 16, v88
	v_mul_f32_e32 v140, v156, v121
	v_fmac_f32_e32 v140, v157, v120
	v_lshlrev_b32_e32 v156, 16, v89
	v_and_b32_e32 v157, 0xffff0000, v89
	v_fmac_f32_e32 v140, v156, v122
	v_fmac_f32_e32 v140, v157, v123
	v_lshlrev_b32_e32 v156, 16, v90
	v_and_b32_e32 v157, 0xffff0000, v90
	v_fmac_f32_e32 v140, v156, v124
	v_fmac_f32_e32 v140, v157, v125
	v_lshlrev_b32_e32 v156, 16, v91
	v_and_b32_e32 v157, 0xffff0000, v91
	v_fmac_f32_e32 v140, v156, v126
	v_fmac_f32_e32 v140, v157, v127
	v_and_b32_e32 v156, 0xffff0000, v92
	v_lshlrev_b32_e32 v157, 16, v92
	v_mul_f32_e32 v148, v156, v129
	v_fmac_f32_e32 v148, v157, v128
	v_lshlrev_b32_e32 v156, 16, v93
	v_and_b32_e32 v157, 0xffff0000, v93
	v_fmac_f32_e32 v148, v156, v130
	v_fmac_f32_e32 v148, v157, v131
	v_lshlrev_b32_e32 v156, 16, v94
	v_and_b32_e32 v157, 0xffff0000, v94
	v_fmac_f32_e32 v148, v156, v132
	v_fmac_f32_e32 v148, v157, v133
	v_lshlrev_b32_e32 v156, 16, v95
	v_and_b32_e32 v157, 0xffff0000, v95
	v_fmac_f32_e32 v148, v156, v134
	v_fmac_f32_e32 v148, v157, v135
	v_add_f32_e32 v140, 0, v140
	v_add_f32_e32 v140, v140, v148
	s_waitcnt vmcnt(4)
	v_and_b32_e32 v156, 0xffff0000, v96
	v_lshlrev_b32_e32 v157, 16, v96
	v_mul_f32_e32 v141, v156, v121
	v_fmac_f32_e32 v141, v157, v120
	v_lshlrev_b32_e32 v156, 16, v97
	v_and_b32_e32 v157, 0xffff0000, v97
	v_fmac_f32_e32 v141, v156, v122
	v_fmac_f32_e32 v141, v157, v123
	v_lshlrev_b32_e32 v156, 16, v98
	v_and_b32_e32 v157, 0xffff0000, v98
	v_fmac_f32_e32 v141, v156, v124
	v_fmac_f32_e32 v141, v157, v125
	v_lshlrev_b32_e32 v156, 16, v99
	v_and_b32_e32 v157, 0xffff0000, v99
	v_fmac_f32_e32 v141, v156, v126
	v_fmac_f32_e32 v141, v157, v127
	v_and_b32_e32 v156, 0xffff0000, v100
	v_lshlrev_b32_e32 v157, 16, v100
	v_mul_f32_e32 v149, v156, v129
	v_fmac_f32_e32 v149, v157, v128
	v_lshlrev_b32_e32 v156, 16, v101
	v_and_b32_e32 v157, 0xffff0000, v101
	v_fmac_f32_e32 v149, v156, v130
	v_fmac_f32_e32 v149, v157, v131
	v_lshlrev_b32_e32 v156, 16, v102
	v_and_b32_e32 v157, 0xffff0000, v102
	v_fmac_f32_e32 v149, v156, v132
	v_fmac_f32_e32 v149, v157, v133
	v_lshlrev_b32_e32 v156, 16, v103
	v_and_b32_e32 v157, 0xffff0000, v103
	v_fmac_f32_e32 v149, v156, v134
	v_fmac_f32_e32 v149, v157, v135
	v_add_f32_e32 v141, 0, v141
	v_add_f32_e32 v141, v141, v149
	s_waitcnt vmcnt(2)
	v_and_b32_e32 v156, 0xffff0000, v104
	v_lshlrev_b32_e32 v157, 16, v104
	v_mul_f32_e32 v142, v156, v121
	v_fmac_f32_e32 v142, v157, v120
	v_lshlrev_b32_e32 v156, 16, v105
	v_and_b32_e32 v157, 0xffff0000, v105
	v_fmac_f32_e32 v142, v156, v122
	v_fmac_f32_e32 v142, v157, v123
	v_lshlrev_b32_e32 v156, 16, v106
	v_and_b32_e32 v157, 0xffff0000, v106
	v_fmac_f32_e32 v142, v156, v124
	v_fmac_f32_e32 v142, v157, v125
	v_lshlrev_b32_e32 v156, 16, v107
	v_and_b32_e32 v157, 0xffff0000, v107
	v_fmac_f32_e32 v142, v156, v126
	v_fmac_f32_e32 v142, v157, v127
	v_and_b32_e32 v156, 0xffff0000, v108
	v_lshlrev_b32_e32 v157, 16, v108
	v_mul_f32_e32 v150, v156, v129
	v_fmac_f32_e32 v150, v157, v128
	v_lshlrev_b32_e32 v156, 16, v109
	v_and_b32_e32 v157, 0xffff0000, v109
	v_fmac_f32_e32 v150, v156, v130
	v_fmac_f32_e32 v150, v157, v131
	v_lshlrev_b32_e32 v156, 16, v110
	v_and_b32_e32 v157, 0xffff0000, v110
	v_fmac_f32_e32 v150, v156, v132
	v_fmac_f32_e32 v150, v157, v133
	v_lshlrev_b32_e32 v156, 16, v111
	v_and_b32_e32 v157, 0xffff0000, v111
	v_fmac_f32_e32 v150, v156, v134
	v_fmac_f32_e32 v150, v157, v135
	v_add_f32_e32 v142, 0, v142
	v_add_f32_e32 v142, v142, v150
	s_waitcnt vmcnt(0)
; __device__ __forceinline__ float bf_lo(unsigned u) { return __uint_as_float(u << 16); }
; __device__ __forceinline__ float bf_hi(unsigned u) { return __uint_as_float(u & 0xffff0000u); }
; __device__ __forceinline__ void phase_ych(const bf16_t* A2, const bf16_t* Wc, float* YCH) {
;     ...
;             acc += bf_lo(av.x) * bf_lo(wv.x) + bf_hi(av.x) * bf_hi(wv.x) + bf_lo(av.y) * bf_lo(wv.y) + bf_hi(av.y) * bf_hi(wv.y) + bf_lo(av.z) * bf_lo(wv.z) + bf_hi(av.z) * bf_hi(wv.z) + bf_lo(av.w) * bf_lo(wv.w) + bf_hi(av.w) * bf_hi(wv.w); }
; #pragma unroll
;         for (int sft = 32; sft >= 1; sft >>= 1) acc += __shfl_xor(acc, sft);
;         if (lane == 0) YCH[o] = acc;
	v_and_b32_e32 v156, 0xffff0000, v112
	v_lshlrev_b32_e32 v157, 16, v112
	v_mul_f32_e32 v143, v156, v121
	v_fmac_f32_e32 v143, v157, v120
	v_lshlrev_b32_e32 v156, 16, v113
	v_and_b32_e32 v157, 0xffff0000, v113
	v_fmac_f32_e32 v143, v156, v122
	v_fmac_f32_e32 v143, v157, v123
	v_lshlrev_b32_e32 v156, 16, v114
	v_and_b32_e32 v157, 0xffff0000, v114
	v_fmac_f32_e32 v143, v156, v124
	v_fmac_f32_e32 v143, v157, v125
	v_lshlrev_b32_e32 v156, 16, v115
	v_and_b32_e32 v157, 0xffff0000, v115
	v_fmac_f32_e32 v143, v156, v126
	v_fmac_f32_e32 v143, v157, v127
	v_and_b32_e32 v156, 0xffff0000, v116
	v_lshlrev_b32_e32 v157, 16, v116
	v_mul_f32_e32 v151, v156, v129
	v_fmac_f32_e32 v151, v157, v128
	v_lshlrev_b32_e32 v156, 16, v117
	v_and_b32_e32 v157, 0xffff0000, v117
	v_fmac_f32_e32 v151, v156, v130
	v_fmac_f32_e32 v151, v157, v131
	v_lshlrev_b32_e32 v156, 16, v118
	v_and_b32_e32 v157, 0xffff0000, v118
	v_fmac_f32_e32 v151, v156, v132
	v_fmac_f32_e32 v151, v157, v133
	v_lshlrev_b32_e32 v156, 16, v119
	v_and_b32_e32 v157, 0xffff0000, v119
	v_fmac_f32_e32 v151, v156, v134
	v_fmac_f32_e32 v151, v157, v135
	v_add_f32_e32 v143, 0, v143
	v_add_f32_e32 v143, v143, v151
	ds_bpermute_b32 v160, v8, v136
	ds_bpermute_b32 v161, v8, v137
	ds_bpermute_b32 v162, v8, v138
	ds_bpermute_b32 v163, v8, v139
	ds_bpermute_b32 v164, v8, v140
	ds_bpermute_b32 v165, v8, v141
	ds_bpermute_b32 v166, v8, v142
	ds_bpermute_b32 v167, v8, v143
	s_waitcnt lgkmcnt(0)
	v_add_f32_e32 v136, v136, v160
	v_add_f32_e32 v137, v137, v161
	v_add_f32_e32 v138, v138, v162
	v_add_f32_e32 v139, v139, v163
	v_add_f32_e32 v140, v140, v164
	v_add_f32_e32 v141, v141, v165
	v_add_f32_e32 v142, v142, v166
	v_add_f32_e32 v143, v143, v167
	ds_bpermute_b32 v160, v9, v136
	ds_bpermute_b32 v161, v9, v137
	ds_bpermute_b32 v162, v9, v138
	ds_bpermute_b32 v163, v9, v139
	ds_bpermute_b32 v164, v9, v140
	ds_bpermute_b32 v165, v9, v141
	ds_bpermute_b32 v166, v9, v142
	ds_bpermute_b32 v167, v9, v143
	s_waitcnt lgkmcnt(0)
	v_add_f32_e32 v136, v136, v160
	v_add_f32_e32 v137, v137, v161
	v_add_f32_e32 v138, v138, v162
	v_add_f32_e32 v139, v139, v163
	v_add_f32_e32 v140, v140, v164
	v_add_f32_e32 v141, v141, v165
	v_add_f32_e32 v142, v142, v166
	v_add_f32_e32 v143, v143, v167
	ds_bpermute_b32 v160, v10, v136
	ds_bpermute_b32 v161, v10, v137
	ds_bpermute_b32 v162, v10, v138
	ds_bpermute_b32 v163, v10, v139
	ds_bpermute_b32 v164, v10, v140
	ds_bpermute_b32 v165, v10, v141
	ds_bpermute_b32 v166, v10, v142
	ds_bpermute_b32 v167, v10, v143
	s_waitcnt lgkmcnt(0)
	v_add_f32_e32 v136, v136, v160
	v_add_f32_e32 v137, v137, v161
	v_add_f32_e32 v138, v138, v162
	v_add_f32_e32 v139, v139, v163
	v_add_f32_e32 v140, v140, v164
	v_add_f32_e32 v141, v141, v165
	v_add_f32_e32 v142, v142, v166
	v_add_f32_e32 v143, v143, v167
	ds_bpermute_b32 v160, v11, v136
	ds_bpermute_b32 v161, v11, v137
	ds_bpermute_b32 v162, v11, v138
	ds_bpermute_b32 v163, v11, v139
	ds_bpermute_b32 v164, v11, v140
	ds_bpermute_b32 v165, v11, v141
	ds_bpermute_b32 v166, v11, v142
	ds_bpermute_b32 v167, v11, v143
	s_waitcnt lgkmcnt(0)
	v_add_f32_e32 v136, v136, v160
	v_add_f32_e32 v137, v137, v161
	v_add_f32_e32 v138, v138, v162
	v_add_f32_e32 v139, v139, v163
	v_add_f32_e32 v140, v140, v164
	v_add_f32_e32 v141, v141, v165
	v_add_f32_e32 v142, v142, v166
	v_add_f32_e32 v143, v143, v167
	ds_bpermute_b32 v160, v12, v136
	ds_bpermute_b32 v161, v12, v137
	ds_bpermute_b32 v162, v12, v138
	ds_bpermute_b32 v163, v12, v139
	ds_bpermute_b32 v164, v12, v140
	ds_bpermute_b32 v165, v12, v141
	ds_bpermute_b32 v166, v12, v142
	ds_bpermute_b32 v167, v12, v143
	s_waitcnt lgkmcnt(0)
	v_add_f32_e32 v136, v136, v160
	v_add_f32_e32 v137, v137, v161
	v_add_f32_e32 v138, v138, v162
	v_add_f32_e32 v139, v139, v163
	v_add_f32_e32 v140, v140, v164
	v_add_f32_e32 v141, v141, v165
	v_add_f32_e32 v142, v142, v166
	v_add_f32_e32 v143, v143, v167
	ds_bpermute_b32 v160, v13, v136
	ds_bpermute_b32 v161, v13, v137
	ds_bpermute_b32 v162, v13, v138
	ds_bpermute_b32 v163, v13, v139
	ds_bpermute_b32 v164, v13, v140
	ds_bpermute_b32 v165, v13, v141
	ds_bpermute_b32 v166, v13, v142
	ds_bpermute_b32 v167, v13, v143
	s_waitcnt lgkmcnt(0)
	v_add_f32_e32 v136, v136, v160
	v_add_f32_e32 v137, v137, v161
	v_add_f32_e32 v138, v138, v162
	v_add_f32_e32 v139, v139, v163
	v_add_f32_e32 v140, v140, v164
	v_add_f32_e32 v141, v141, v165
	v_add_f32_e32 v142, v142, v166
	v_add_f32_e32 v143, v143, v167
	s_and_saveexec_b64 s[8:9], s[2:3]
	global_store_dword v155, v136, s[60:61]
	v_add_u32_e32 v155, 0x2000, v155
	global_store_dword v155, v137, s[60:61]
	v_add_u32_e32 v155, 0x2000, v155
	global_store_dword v155, v138, s[60:61]
	v_add_u32_e32 v155, 0x2000, v155
	global_store_dword v155, v139, s[60:61]
	v_add_u32_e32 v155, 0x2000, v155
	global_store_dword v155, v140, s[60:61]
	v_add_u32_e32 v155, 0x2000, v155
	global_store_dword v155, v141, s[60:61]
	v_add_u32_e32 v155, 0x2000, v155
	global_store_dword v155, v142, s[60:61]
	v_add_u32_e32 v155, 0x2000, v155
	global_store_dword v155, v143, s[60:61]
	s_or_b64 exec, exec, s[8:9]
	s_branch .LBB0_570
